# speedup vs baseline: 1.0019x; 1.0019x over previous
; DEV void gemm_phase(const GemmJob& J) {
;   const int nM = J.M / BM, nN = J.N / BM, nwg = nM * nN;
;   const int nsub = (J.mode == 2) ? 2 : 1;
;   const int niter = ((nwg - (int)blockIdx.x + (int)gridDim.x - 1) / (int)gridDim.x) * nsub;
; __global__ void __launch_bounds__(512, 2) mega(Params p) {
;     ...
;     if (g1 || g4 || g5 || g7 || g8) {
;       GemmJob J;
;       J.M = GT;
;       J.A = g4 ? p.oA : (g8 ? p.ha : p.h);
;       J.lda = g4 ? 512 : (g8 ? 4096 : 1024);
;       J.Bt = wl + (g1 ? W_IN : (g4 ? W_A : (g5 ? W_O : (g7 ? W_1 : W_2))));
;       J.K = g4 ? 512 : (g8 ? 4096 : 1024);
;       J.A2 = p.oB; J.lda2 = 2048; J.Bt2 = wl + W_B; J.K2 = 1024;
;       J.N = g1 ? LDP : (g7 ? 4096 : 1024);
;       J.mode = g1 ? 1 : (g4 ? 2 : (g7 ? 4 : 3));
;       J.obf = g4 ? p.h : (g1 ? p.proj : p.ha);
;       J.ha = p.ha; J.hsplit = g1 ? NHA : 0; J.cofs = g1 ? NHA : 0;
;       J.ldo = g1 ? LDR : (g7 ? 4096 : 1024);
;       J.of32 = xo;
;       J.res = g5 ? xcur : xo;
;       J.gate = p.proj;
;       J.bf = p.bgf + layer * 512; J.bb = p.bgb + layer * 512;
.LBB0_177:
	s_and_b64 vcc, exec, s[0:1]
	s_cbranch_vccz .LBB0_435
	s_cmp_eq_u32 s63, 4
	s_cselect_b64 s[14:15], -1, 0
	s_cmp_eq_u32 s63, 7
	s_cselect_b64 s[0:1], -1, 0
	s_and_b64 s[6:7], s[0:1], exec
	s_movk_i32 s6, 0x400
	s_cselect_b32 s8, 0x1000, s6
	s_lshr_b32 s9, s8, 8
	s_cmp_eq_u32 s63, 1
	s_cselect_b64 s[90:91], -1, 0
	s_and_b64 s[6:7], s[90:91], exec
	s_cselect_b32 s6, 42, s9
	s_mul_i32 s7, s6, s52
	v_readlane_b32 s9, v254, 44
	s_add_i32 s9, s9, s7
	s_ashr_i32 s10, s9, 31
	v_readlane_b32 s11, v254, 55
	s_xor_b32 s10, s10, s11
	s_abs_i32 s9, s9
	v_readlane_b32 s11, v254, 57
	s_mul_hi_u32 s11, s9, s11
	v_readlane_b32 s16, v254, 56
	s_mul_i32 s12, s11, s16
	s_sub_i32 s9, s9, s12
	s_add_i32 s12, s11, 1
	s_sub_i32 s13, s9, s16
	s_cmp_ge_u32 s9, s16
	s_cselect_b32 s11, s12, s11
	s_cselect_b32 s9, s13, s9
	s_add_i32 s12, s11, 1
	s_cmp_ge_u32 s9, s16
	s_cselect_b32 s9, s12, s11
	v_cndmask_b32_e64 v147, 0, 1, s[14:15]
	s_xor_b32 s9, s9, s10
	s_sub_i32 s9, s9, s10
	v_readfirstlane_b32 s42, v147
	s_lshl_b32 s43, s9, s42
	s_cmp_lt_i32 s43, 1
	s_cbranch_scc1 .LBB0_435
	s_and_b64 s[10:11], s[30:31], exec
	s_cselect_b32 s9, 0x2a00000, 0
	s_add_u32 s9, s70, s9
	s_addc_u32 s23, s71, 0
	s_cmp_eq_u32 s63, 5
	s_cselect_b64 s[10:11], -1, 0
	s_cmp_eq_u32 s63, 8
	s_cselect_b64 s[12:13], -1, 0
	s_and_b64 s[18:19], s[12:13], exec
	s_cselect_b32 s20, s74, s72
	s_cselect_b32 s21, s75, s73
	s_and_b64 s[18:19], s[14:15], exec
	s_cselect_b32 s47, s79, s21
	s_cselect_b32 s46, s78, s20
	s_and_b64 s[12:13], s[12:13], exec
	s_movk_i32 s12, 0x400
	s_cselect_b32 s20, 0x1000, s12
	s_and_b64 s[12:13], s[14:15], exec
	s_cselect_b32 s44, 0x200, s20
	s_and_b64 s[12:13], s[0:1], exec
	s_mov_b32 s12, 0xd00000
	s_cselect_b32 s20, s12, 0x1100000
	s_and_b64 s[12:13], s[10:11], exec
	s_cselect_b32 s20, 0xc00000, s20
	s_and_b64 s[12:13], s[14:15], exec
	s_cselect_b32 s20, 0xa80000, s20
	s_and_b64 s[12:13], s[90:91], exec
	s_cselect_b32 s12, 0, s20
	s_lshl_b32 s12, s12, 1
	s_add_u32 s50, s9, s12
	s_addc_u32 s51, s23, 0
	s_add_u32 s88, s9, 0x1600000
	s_addc_u32 s89, s23, 0
	s_and_b64 s[12:13], s[90:91], exec
	s_cselect_b32 s9, s76, s74
	s_cselect_b32 s24, s77, s75
	s_and_b64 s[12:13], s[14:15], exec
	s_cselect_b32 s37, s73, s24
	s_cselect_b32 s36, s72, s9
	s_and_b64 s[12:13], s[90:91], exec
	s_cselect_b32 s45, 0x1200, 0
	s_and_b64 s[10:11], s[10:11], exec
	s_cselect_b32 s99, s49, s93
	s_cselect_b32 s98, s48, s92
	s_and_b64 s[10:11], s[30:31], exec
	v_readlane_b32 s16, v254, 6
	s_cselect_b32 s9, 0x800, 0
	v_readlane_b32 s26, v254, 16
	v_readlane_b32 s17, v254, 7
	v_readlane_b32 s27, v254, 17
	s_add_u32 s16, s26, s9
	v_readlane_b32 s22, v254, 12
	v_readlane_b32 s30, v254, 20
	s_addc_u32 s17, s27, 0
	v_readlane_b32 s23, v254, 13
	v_readlane_b32 s31, v254, 21
	s_add_u32 s22, s30, s9
	s_addc_u32 s23, s31, 0
	s_and_b64 s[10:11], s[90:91], exec
	s_cselect_b32 s26, 0x1800, s8
	s_and_b64 s[0:1], s[0:1], exec
	s_cselect_b32 s8, 4, 3
	s_and_b64 s[0:1], s[14:15], exec
	s_cselect_b32 s8, 2, s8
	s_and_b64 s[0:1], s[90:91], exec
	s_cselect_b32 s0, 1, s8
	s_ashr_i32 s1, s7, 31
	s_lshr_b32 s1, s1, 29
	s_add_i32 s1, s7, s1
	v_readlane_b32 s24, v254, 14
	s_ashr_i32 s64, s1, 3
	s_and_b32 s1, s1, -8
	s_sub_i32 s65, s7, s1
	s_add_i32 s31, s64, 1
	s_lshl_b32 s24, s6, 2
	s_xor_b64 s[96:97], s[14:15], -1
	v_readlane_b32 s18, v254, 8
	v_readlane_b32 s19, v254, 9
	s_cmp_lg_u32 s0, 3
	v_readlane_b32 s25, v254, 15
	s_cselect_b64 s[18:19], -1, 0
	s_cmp_lg_u32 s0, 4
	s_cselect_b64 s[58:59], -1, 0
	s_abs_i32 s25, s24
	v_cvt_f32_u32_e32 v0, s25
	s_sub_i32 s0, 0, s25
	v_readlane_b32 s20, v254, 10
	v_readlane_b32 s21, v254, 11
	v_rcp_iflag_f32_e32 v0, v0
	s_mov_b64 s[20:21], s[36:37]
	s_mov_b32 s94, 0
	s_lshl_b32 s30, s26, 1
	v_mul_f32_e32 v0, 0x4f7ffffe, v0
	v_cvt_u32_f32_e32 v0, v0
	s_bfe_i32 s95, s6, 0x1001d
	v_readlane_b32 s28, v254, 18
	v_readlane_b32 s29, v254, 19
	v_readfirstlane_b32 s1, v0
	s_mul_i32 s0, s0, s1
	s_mul_hi_u32 s0, s1, s0
	s_add_i32 s66, s1, s0
	s_cmp_lt_u32 s43, 8
	s_cbranch_scc1 .Lstag_done
	s_and_b32 s0, s2, 7
	s_cmp_eq_u32 s0, 0
	s_cbranch_scc1 .Lstag_done
.Lstag_loop:
	s_sleep 16
	s_add_i32 s0, s0, -1
	s_cmp_lg_u32 s0, 0
	s_cbranch_scc1 .Lstag_loop
.Lstag_done:
	s_branch .LBB0_181
.LBB0_180:
	s_add_i32 s94, s94, 1
	s_cmp_eq_u32 s94, s43
	s_cbranch_scc1 .LBB0_434
